# P6 second epilogue loop hand-written: DPP row_ror:8 lane re-pairing, x1 stores cover 8 rows x 128 B and XN stores 8 rows x 64 B per instruction, gate/shift vectors loaded before the closing barrier of
# speedup vs baseline: 1.0087x; 1.0087x over previous
; __device__ __forceinline__ unsigned cvt_pk_bf16(float lo, float hi) { unsigned r; asm volatile("v_cvt_pk_bf16_f32 %0, %1, %2" : "=v"(r) : "v"(lo), "v"(hi)); return r; }
;     __device__ __forceinline__ void fused(f32x4 (&acc)[2][2][4][2], const Unit& u, int wr, int wc, int fr, int fq, PG8_LAS unsigned char* lds, int wid, int lane) const {
;     ...
;         {
;             f32x4 g[2][2], sv[2][2];
; #pragma unroll
;             for (int bj = 0; bj < 2; ++bj)
; #pragma unroll
;                 for (int n = 0; n < 2; ++n) { g[bj][n] = *(const f32x4*)(gv2 + col0 + bj * HALF + n * 16); sv[bj][n] = *(const f32x4*)(sv2 + col0 + bj * HALF + n * 16); }
; #pragma unroll
;             for (int ai = 0; ai < 2; ++ai)
; #pragma unroll
;                 for (int m = 0; m < 4; ++m) { const int r = ai * HALF + wr * 64 + m * 16 + fr; const float rs = S[r]; const size_t off = (size_t)(row_off + u.pm * BM + r) * DM + col0;
; #pragma unroll
;                     for (int bj = 0; bj < 2; ++bj)
; #pragma unroll
;                         for (int n = 0; n < 2; ++n) { const f32x4 x1 = acc[ai][bj][m][n]; *(f32x4*)(out + off + bj * HALF + n * 16) = x1;
;                             const f32x4 o = x1 * rs * g[bj][n] + sv[bj][n]; u32x2 w; w.x = cvt_pk_bf16(o[0], o[1]); w.y = cvt_pk_bf16(o[2], o[3]); *(u32x2*)(xn + off + bj * HALF + n * 16) = w; }
;                     asm volatile("" ::: "memory"); }
.LBB0_735:
	s_or_b64 exec, exec, s[10:11]
	v_and_b32_e32 v192, 8, v195
	v_lshlrev_b32_e32 v193, 2, v166
	v_lshl_add_u32 v193, v192, 3, v193
	s_add_u32 s24, s52, 0x8000
	s_addc_u32 s25, s53, 0
	s_add_u32 s92, s52, 0x10000
	s_addc_u32 s93, s53, 0
	s_add_u32 s94, s14, 0x2000000
	s_addc_u32 s95, s15, 0
	global_load_dwordx4 v[128:131], v193, s[24:25]
	global_load_dwordx4 v[132:135], v193, s[24:25] offset:512
	global_load_dwordx4 v[136:139], v193, s[92:93]
	global_load_dwordx4 v[140:143], v193, s[92:93] offset:512
	v_sub_u32_e32 v193, v178, v192
	v_lshlrev_b32_e32 v176, 12, v193
	v_lshl_add_u32 v176, v166, 2, v176
	v_lshl_add_u32 v176, v192, 3, v176
	v_lshlrev_b32_e32 v177, 11, v193
	v_lshl_add_u32 v177, v166, 1, v177
	v_lshl_add_u32 v177, v192, 2, v177
	v_lshlrev_b32_e32 v179, 2, v192
	v_sub_u32_e32 v179, v160, v179
	v_add_u32_e32 v179, 0x1000, v179
	s_waitcnt lgkmcnt(0)
	s_barrier
	ds_read2_b32 v[144:145], v179 offset0:0 offset1:8
	ds_read2_b32 v[146:147], v179 offset0:16 offset1:24
	ds_read2_b32 v[148:149], v179 offset0:32 offset1:40
	ds_read2_b32 v[150:151], v179 offset0:48 offset1:56
	ds_read2_b32 v[152:153], v179 offset0:128 offset1:136
	ds_read2_b32 v[154:155], v179 offset0:144 offset1:152
	ds_read2_b32 v[156:157], v179 offset0:160 offset1:168
	ds_read2_b32 v[158:159], v179 offset0:176 offset1:184
	v_mov_b32_e32 v188, v124
	v_mov_b32_e32 v189, v125
	v_mov_b32_e32 v190, v126
	v_mov_b32_e32 v191, v127
	v_mov_b32_dpp v124, v120 row_ror:8 row_mask:0xf bank_mask:0xc
	v_mov_b32_dpp v125, v121 row_ror:8 row_mask:0xf bank_mask:0xc
	v_mov_b32_dpp v126, v122 row_ror:8 row_mask:0xf bank_mask:0xc
	v_mov_b32_dpp v127, v123 row_ror:8 row_mask:0xf bank_mask:0xc
	v_mov_b32_dpp v120, v188 row_ror:8 row_mask:0xf bank_mask:0x3
	v_mov_b32_dpp v121, v189 row_ror:8 row_mask:0xf bank_mask:0x3
	v_mov_b32_dpp v122, v190 row_ror:8 row_mask:0xf bank_mask:0x3
	v_mov_b32_dpp v123, v191 row_ror:8 row_mask:0xf bank_mask:0x3
	v_mov_b32_e32 v192, v176
	v_add_u32_e32 v193, 0x8000, v176
	global_store_dwordx4 v192, v[124:127], s[12:13] nt
	global_store_dwordx4 v193, v[120:123], s[12:13] nt
	s_waitcnt vmcnt(2) lgkmcnt(0)
	v_mul_f32_e32 v196, v124, v144
	v_mul_f32_e32 v197, v125, v144
	v_mul_f32_e32 v198, v126, v144
	v_mul_f32_e32 v199, v127, v144
	v_mul_f32_e32 v200, v120, v145
	v_mul_f32_e32 v201, v121, v145
	v_mul_f32_e32 v202, v122, v145
	v_mul_f32_e32 v203, v123, v145
	v_fma_f32 v196, v196, v128, v136
	v_fma_f32 v197, v197, v129, v137
	v_fma_f32 v198, v198, v130, v138
	v_fma_f32 v199, v199, v131, v139
	v_fma_f32 v200, v200, v128, v136
	v_fma_f32 v201, v201, v129, v137
	v_fma_f32 v202, v202, v130, v138
	v_fma_f32 v203, v203, v131, v139
	v_cvt_pk_bf16_f32 v196, v196, v197
	v_cvt_pk_bf16_f32 v197, v198, v199
	v_cvt_pk_bf16_f32 v200, v200, v201
	v_cvt_pk_bf16_f32 v201, v202, v203
	v_mov_b32_e32 v192, v177
	v_add_u32_e32 v193, 0x4000, v177
	global_store_dwordx2 v192, v[196:197], s[94:95]
	global_store_dwordx2 v193, v[200:201], s[94:95]
	v_mov_b32_e32 v188, v116
	v_mov_b32_e32 v189, v117
	v_mov_b32_e32 v190, v118
	v_mov_b32_e32 v191, v119
	v_mov_b32_dpp v116, v112 row_ror:8 row_mask:0xf bank_mask:0xc
	v_mov_b32_dpp v117, v113 row_ror:8 row_mask:0xf bank_mask:0xc
	v_mov_b32_dpp v118, v114 row_ror:8 row_mask:0xf bank_mask:0xc
	v_mov_b32_dpp v119, v115 row_ror:8 row_mask:0xf bank_mask:0xc
	v_mov_b32_dpp v112, v188 row_ror:8 row_mask:0xf bank_mask:0x3
	v_mov_b32_dpp v113, v189 row_ror:8 row_mask:0xf bank_mask:0x3
	v_mov_b32_dpp v114, v190 row_ror:8 row_mask:0xf bank_mask:0x3
	v_mov_b32_dpp v115, v191 row_ror:8 row_mask:0xf bank_mask:0x3
	v_mov_b32_e32 v192, v176
	v_add_u32_e32 v193, 0x8000, v176
	global_store_dwordx4 v192, v[116:119], s[12:13] offset:512 nt
	global_store_dwordx4 v193, v[112:115], s[12:13] offset:512 nt
	v_mul_f32_e32 v196, v116, v144
	v_mul_f32_e32 v197, v117, v144
	v_mul_f32_e32 v198, v118, v144
	v_mul_f32_e32 v199, v119, v144
	v_mul_f32_e32 v200, v112, v145
	v_mul_f32_e32 v201, v113, v145
	v_mul_f32_e32 v202, v114, v145
	v_mul_f32_e32 v203, v115, v145
	v_fma_f32 v196, v196, v132, v140
	v_fma_f32 v197, v197, v133, v141
	v_fma_f32 v198, v198, v134, v142
	v_fma_f32 v199, v199, v135, v143
	v_fma_f32 v200, v200, v132, v140
	v_fma_f32 v201, v201, v133, v141
	v_fma_f32 v202, v202, v134, v142
	v_fma_f32 v203, v203, v135, v143
	v_cvt_pk_bf16_f32 v196, v196, v197
	v_cvt_pk_bf16_f32 v197, v198, v199
	v_cvt_pk_bf16_f32 v200, v200, v201
	v_cvt_pk_bf16_f32 v201, v202, v203
	v_mov_b32_e32 v192, v177
	v_add_u32_e32 v193, 0x4000, v177
	global_store_dwordx2 v192, v[196:197], s[94:95] offset:256
	global_store_dwordx2 v193, v[200:201], s[94:95] offset:256
	v_mov_b32_e32 v188, v108
	v_mov_b32_e32 v189, v109
	v_mov_b32_e32 v190, v110
	v_mov_b32_e32 v191, v111
	v_mov_b32_dpp v108, v104 row_ror:8 row_mask:0xf bank_mask:0xc
	v_mov_b32_dpp v109, v105 row_ror:8 row_mask:0xf bank_mask:0xc
	v_mov_b32_dpp v110, v106 row_ror:8 row_mask:0xf bank_mask:0xc
	v_mov_b32_dpp v111, v107 row_ror:8 row_mask:0xf bank_mask:0xc
	v_mov_b32_dpp v104, v188 row_ror:8 row_mask:0xf bank_mask:0x3
	v_mov_b32_dpp v105, v189 row_ror:8 row_mask:0xf bank_mask:0x3
	v_mov_b32_dpp v106, v190 row_ror:8 row_mask:0xf bank_mask:0x3
	v_mov_b32_dpp v107, v191 row_ror:8 row_mask:0xf bank_mask:0x3
	v_add_u32_e32 v192, 0x10000, v176
	v_add_u32_e32 v193, 0x18000, v176
	global_store_dwordx4 v192, v[108:111], s[12:13] nt
	global_store_dwordx4 v193, v[104:107], s[12:13] nt
	v_mul_f32_e32 v196, v108, v146
	v_mul_f32_e32 v197, v109, v146
	v_mul_f32_e32 v198, v110, v146
	v_mul_f32_e32 v199, v111, v146
	v_mul_f32_e32 v200, v104, v147
	v_mul_f32_e32 v201, v105, v147
	v_mul_f32_e32 v202, v106, v147
	v_mul_f32_e32 v203, v107, v147
; __device__ __forceinline__ unsigned cvt_pk_bf16(float lo, float hi) { unsigned r; asm volatile("v_cvt_pk_bf16_f32 %0, %1, %2" : "=v"(r) : "v"(lo), "v"(hi)); return r; }
;     __device__ __forceinline__ void fused(f32x4 (&acc)[2][2][4][2], const Unit& u, int wr, int wc, int fr, int fq, PG8_LAS unsigned char* lds, int wid, int lane) const {
;     ...
;         {
;             f32x4 g[2][2], sv[2][2];
; #pragma unroll
;             for (int bj = 0; bj < 2; ++bj)
; #pragma unroll
;                 for (int n = 0; n < 2; ++n) { g[bj][n] = *(const f32x4*)(gv2 + col0 + bj * HALF + n * 16); sv[bj][n] = *(const f32x4*)(sv2 + col0 + bj * HALF + n * 16); }
; #pragma unroll
;             for (int ai = 0; ai < 2; ++ai)
; #pragma unroll
;                 for (int m = 0; m < 4; ++m) { const int r = ai * HALF + wr * 64 + m * 16 + fr; const float rs = S[r]; const size_t off = (size_t)(row_off + u.pm * BM + r) * DM + col0;
; #pragma unroll
;                     for (int bj = 0; bj < 2; ++bj)
; #pragma unroll
;                         for (int n = 0; n < 2; ++n) { const f32x4 x1 = acc[ai][bj][m][n]; *(f32x4*)(out + off + bj * HALF + n * 16) = x1;
;                             const f32x4 o = x1 * rs * g[bj][n] + sv[bj][n]; u32x2 w; w.x = cvt_pk_bf16(o[0], o[1]); w.y = cvt_pk_bf16(o[2], o[3]); *(u32x2*)(xn + off + bj * HALF + n * 16) = w; }
;                     asm volatile("" ::: "memory"); }
	v_fma_f32 v196, v196, v128, v136
	v_fma_f32 v197, v197, v129, v137
	v_fma_f32 v198, v198, v130, v138
	v_fma_f32 v199, v199, v131, v139
	v_fma_f32 v200, v200, v128, v136
	v_fma_f32 v201, v201, v129, v137
	v_fma_f32 v202, v202, v130, v138
	v_fma_f32 v203, v203, v131, v139
	v_cvt_pk_bf16_f32 v196, v196, v197
	v_cvt_pk_bf16_f32 v197, v198, v199
	v_cvt_pk_bf16_f32 v200, v200, v201
	v_cvt_pk_bf16_f32 v201, v202, v203
	v_add_u32_e32 v192, 0x8000, v177
	v_add_u32_e32 v193, 0xc000, v177
	global_store_dwordx2 v192, v[196:197], s[94:95]
	global_store_dwordx2 v193, v[200:201], s[94:95]
	v_mov_b32_e32 v188, v100
	v_mov_b32_e32 v189, v101
	v_mov_b32_e32 v190, v102
	v_mov_b32_e32 v191, v103
	v_mov_b32_dpp v100, v96 row_ror:8 row_mask:0xf bank_mask:0xc
	v_mov_b32_dpp v101, v97 row_ror:8 row_mask:0xf bank_mask:0xc
	v_mov_b32_dpp v102, v98 row_ror:8 row_mask:0xf bank_mask:0xc
	v_mov_b32_dpp v103, v99 row_ror:8 row_mask:0xf bank_mask:0xc
	v_mov_b32_dpp v96, v188 row_ror:8 row_mask:0xf bank_mask:0x3
	v_mov_b32_dpp v97, v189 row_ror:8 row_mask:0xf bank_mask:0x3
	v_mov_b32_dpp v98, v190 row_ror:8 row_mask:0xf bank_mask:0x3
	v_mov_b32_dpp v99, v191 row_ror:8 row_mask:0xf bank_mask:0x3
	v_add_u32_e32 v192, 0x10000, v176
	v_add_u32_e32 v193, 0x18000, v176
	global_store_dwordx4 v192, v[100:103], s[12:13] offset:512 nt
	global_store_dwordx4 v193, v[96:99], s[12:13] offset:512 nt
	v_mul_f32_e32 v196, v100, v146
	v_mul_f32_e32 v197, v101, v146
	v_mul_f32_e32 v198, v102, v146
	v_mul_f32_e32 v199, v103, v146
	v_mul_f32_e32 v200, v96, v147
	v_mul_f32_e32 v201, v97, v147
	v_mul_f32_e32 v202, v98, v147
	v_mul_f32_e32 v203, v99, v147
	v_fma_f32 v196, v196, v132, v140
	v_fma_f32 v197, v197, v133, v141
	v_fma_f32 v198, v198, v134, v142
	v_fma_f32 v199, v199, v135, v143
	v_fma_f32 v200, v200, v132, v140
	v_fma_f32 v201, v201, v133, v141
	v_fma_f32 v202, v202, v134, v142
	v_fma_f32 v203, v203, v135, v143
	v_cvt_pk_bf16_f32 v196, v196, v197
	v_cvt_pk_bf16_f32 v197, v198, v199
	v_cvt_pk_bf16_f32 v200, v200, v201
	v_cvt_pk_bf16_f32 v201, v202, v203
	v_add_u32_e32 v192, 0x8000, v177
	v_add_u32_e32 v193, 0xc000, v177
	global_store_dwordx2 v192, v[196:197], s[94:95] offset:256
	global_store_dwordx2 v193, v[200:201], s[94:95] offset:256
	v_mov_b32_e32 v188, v92
	v_mov_b32_e32 v189, v93
	v_mov_b32_e32 v190, v94
	v_mov_b32_e32 v191, v95
	v_mov_b32_dpp v92, v88 row_ror:8 row_mask:0xf bank_mask:0xc
	v_mov_b32_dpp v93, v89 row_ror:8 row_mask:0xf bank_mask:0xc
	v_mov_b32_dpp v94, v90 row_ror:8 row_mask:0xf bank_mask:0xc
	v_mov_b32_dpp v95, v91 row_ror:8 row_mask:0xf bank_mask:0xc
	v_mov_b32_dpp v88, v188 row_ror:8 row_mask:0xf bank_mask:0x3
	v_mov_b32_dpp v89, v189 row_ror:8 row_mask:0xf bank_mask:0x3
	v_mov_b32_dpp v90, v190 row_ror:8 row_mask:0xf bank_mask:0x3
	v_mov_b32_dpp v91, v191 row_ror:8 row_mask:0xf bank_mask:0x3
	v_add_u32_e32 v192, 0x20000, v176
	v_add_u32_e32 v193, 0x28000, v176
	global_store_dwordx4 v192, v[92:95], s[12:13] nt
	global_store_dwordx4 v193, v[88:91], s[12:13] nt
	v_mul_f32_e32 v196, v92, v148
	v_mul_f32_e32 v197, v93, v148
	v_mul_f32_e32 v198, v94, v148
	v_mul_f32_e32 v199, v95, v148
	v_mul_f32_e32 v200, v88, v149
	v_mul_f32_e32 v201, v89, v149
	v_mul_f32_e32 v202, v90, v149
	v_mul_f32_e32 v203, v91, v149
	v_fma_f32 v196, v196, v128, v136
	v_fma_f32 v197, v197, v129, v137
	v_fma_f32 v198, v198, v130, v138
	v_fma_f32 v199, v199, v131, v139
	v_fma_f32 v200, v200, v128, v136
	v_fma_f32 v201, v201, v129, v137
	v_fma_f32 v202, v202, v130, v138
	v_fma_f32 v203, v203, v131, v139
	v_cvt_pk_bf16_f32 v196, v196, v197
	v_cvt_pk_bf16_f32 v197, v198, v199
	v_cvt_pk_bf16_f32 v200, v200, v201
	v_cvt_pk_bf16_f32 v201, v202, v203
	v_add_u32_e32 v192, 0x10000, v177
	v_add_u32_e32 v193, 0x14000, v177
	global_store_dwordx2 v192, v[196:197], s[94:95]
	global_store_dwordx2 v193, v[200:201], s[94:95]
	v_mov_b32_e32 v188, v84
	v_mov_b32_e32 v189, v85
	v_mov_b32_e32 v190, v86
	v_mov_b32_e32 v191, v87
	v_mov_b32_dpp v84, v80 row_ror:8 row_mask:0xf bank_mask:0xc
	v_mov_b32_dpp v85, v81 row_ror:8 row_mask:0xf bank_mask:0xc
	v_mov_b32_dpp v86, v82 row_ror:8 row_mask:0xf bank_mask:0xc
	v_mov_b32_dpp v87, v83 row_ror:8 row_mask:0xf bank_mask:0xc
	v_mov_b32_dpp v80, v188 row_ror:8 row_mask:0xf bank_mask:0x3
	v_mov_b32_dpp v81, v189 row_ror:8 row_mask:0xf bank_mask:0x3
	v_mov_b32_dpp v82, v190 row_ror:8 row_mask:0xf bank_mask:0x3
	v_mov_b32_dpp v83, v191 row_ror:8 row_mask:0xf bank_mask:0x3
	v_add_u32_e32 v192, 0x20000, v176
	v_add_u32_e32 v193, 0x28000, v176
	global_store_dwordx4 v192, v[84:87], s[12:13] offset:512 nt
	global_store_dwordx4 v193, v[80:83], s[12:13] offset:512 nt
	v_mul_f32_e32 v196, v84, v148
	v_mul_f32_e32 v197, v85, v148
	v_mul_f32_e32 v198, v86, v148
	v_mul_f32_e32 v199, v87, v148
	v_mul_f32_e32 v200, v80, v149
	v_mul_f32_e32 v201, v81, v149
	v_mul_f32_e32 v202, v82, v149
	v_mul_f32_e32 v203, v83, v149
	v_fma_f32 v196, v196, v132, v140
	v_fma_f32 v197, v197, v133, v141
	v_fma_f32 v198, v198, v134, v142
	v_fma_f32 v199, v199, v135, v143
	v_fma_f32 v200, v200, v132, v140
	v_fma_f32 v201, v201, v133, v141
	v_fma_f32 v202, v202, v134, v142
	v_fma_f32 v203, v203, v135, v143
	v_cvt_pk_bf16_f32 v196, v196, v197
	v_cvt_pk_bf16_f32 v197, v198, v199
	v_cvt_pk_bf16_f32 v200, v200, v201
	v_cvt_pk_bf16_f32 v201, v202, v203
	v_add_u32_e32 v192, 0x10000, v177
	v_add_u32_e32 v193, 0x14000, v177
	global_store_dwordx2 v192, v[196:197], s[94:95] offset:256
	global_store_dwordx2 v193, v[200:201], s[94:95] offset:256
	v_mov_b32_e32 v188, v76
	v_mov_b32_e32 v189, v77
	v_mov_b32_e32 v190, v78
	v_mov_b32_e32 v191, v79
	v_mov_b32_dpp v76, v72 row_ror:8 row_mask:0xf bank_mask:0xc
; __device__ __forceinline__ unsigned cvt_pk_bf16(float lo, float hi) { unsigned r; asm volatile("v_cvt_pk_bf16_f32 %0, %1, %2" : "=v"(r) : "v"(lo), "v"(hi)); return r; }
;     __device__ __forceinline__ void fused(f32x4 (&acc)[2][2][4][2], const Unit& u, int wr, int wc, int fr, int fq, PG8_LAS unsigned char* lds, int wid, int lane) const {
;     ...
;         {
;             f32x4 g[2][2], sv[2][2];
; #pragma unroll
;             for (int bj = 0; bj < 2; ++bj)
; #pragma unroll
;                 for (int n = 0; n < 2; ++n) { g[bj][n] = *(const f32x4*)(gv2 + col0 + bj * HALF + n * 16); sv[bj][n] = *(const f32x4*)(sv2 + col0 + bj * HALF + n * 16); }
; #pragma unroll
;             for (int ai = 0; ai < 2; ++ai)
; #pragma unroll
;                 for (int m = 0; m < 4; ++m) { const int r = ai * HALF + wr * 64 + m * 16 + fr; const float rs = S[r]; const size_t off = (size_t)(row_off + u.pm * BM + r) * DM + col0;
; #pragma unroll
;                     for (int bj = 0; bj < 2; ++bj)
; #pragma unroll
;                         for (int n = 0; n < 2; ++n) { const f32x4 x1 = acc[ai][bj][m][n]; *(f32x4*)(out + off + bj * HALF + n * 16) = x1;
;                             const f32x4 o = x1 * rs * g[bj][n] + sv[bj][n]; u32x2 w; w.x = cvt_pk_bf16(o[0], o[1]); w.y = cvt_pk_bf16(o[2], o[3]); *(u32x2*)(xn + off + bj * HALF + n * 16) = w; }
;                     asm volatile("" ::: "memory"); }
	v_mov_b32_dpp v77, v73 row_ror:8 row_mask:0xf bank_mask:0xc
	v_mov_b32_dpp v78, v74 row_ror:8 row_mask:0xf bank_mask:0xc
	v_mov_b32_dpp v79, v75 row_ror:8 row_mask:0xf bank_mask:0xc
	v_mov_b32_dpp v72, v188 row_ror:8 row_mask:0xf bank_mask:0x3
	v_mov_b32_dpp v73, v189 row_ror:8 row_mask:0xf bank_mask:0x3
	v_mov_b32_dpp v74, v190 row_ror:8 row_mask:0xf bank_mask:0x3
	v_mov_b32_dpp v75, v191 row_ror:8 row_mask:0xf bank_mask:0x3
	v_add_u32_e32 v192, 0x30000, v176
	v_add_u32_e32 v193, 0x38000, v176
	global_store_dwordx4 v192, v[76:79], s[12:13] nt
	global_store_dwordx4 v193, v[72:75], s[12:13] nt
	v_mul_f32_e32 v196, v76, v150
	v_mul_f32_e32 v197, v77, v150
	v_mul_f32_e32 v198, v78, v150
	v_mul_f32_e32 v199, v79, v150
	v_mul_f32_e32 v200, v72, v151
	v_mul_f32_e32 v201, v73, v151
	v_mul_f32_e32 v202, v74, v151
	v_mul_f32_e32 v203, v75, v151
	v_fma_f32 v196, v196, v128, v136
	v_fma_f32 v197, v197, v129, v137
	v_fma_f32 v198, v198, v130, v138
	v_fma_f32 v199, v199, v131, v139
	v_fma_f32 v200, v200, v128, v136
	v_fma_f32 v201, v201, v129, v137
	v_fma_f32 v202, v202, v130, v138
	v_fma_f32 v203, v203, v131, v139
	v_cvt_pk_bf16_f32 v196, v196, v197
	v_cvt_pk_bf16_f32 v197, v198, v199
	v_cvt_pk_bf16_f32 v200, v200, v201
	v_cvt_pk_bf16_f32 v201, v202, v203
	v_add_u32_e32 v192, 0x18000, v177
	v_add_u32_e32 v193, 0x1c000, v177
	global_store_dwordx2 v192, v[196:197], s[94:95]
	global_store_dwordx2 v193, v[200:201], s[94:95]
	v_mov_b32_e32 v188, v68
	v_mov_b32_e32 v189, v69
	v_mov_b32_e32 v190, v70
	v_mov_b32_e32 v191, v71
	v_mov_b32_dpp v68, v64 row_ror:8 row_mask:0xf bank_mask:0xc
	v_mov_b32_dpp v69, v65 row_ror:8 row_mask:0xf bank_mask:0xc
	v_mov_b32_dpp v70, v66 row_ror:8 row_mask:0xf bank_mask:0xc
	v_mov_b32_dpp v71, v67 row_ror:8 row_mask:0xf bank_mask:0xc
	v_mov_b32_dpp v64, v188 row_ror:8 row_mask:0xf bank_mask:0x3
	v_mov_b32_dpp v65, v189 row_ror:8 row_mask:0xf bank_mask:0x3
	v_mov_b32_dpp v66, v190 row_ror:8 row_mask:0xf bank_mask:0x3
	v_mov_b32_dpp v67, v191 row_ror:8 row_mask:0xf bank_mask:0x3
	v_add_u32_e32 v192, 0x30000, v176
	v_add_u32_e32 v193, 0x38000, v176
	global_store_dwordx4 v192, v[68:71], s[12:13] offset:512 nt
	global_store_dwordx4 v193, v[64:67], s[12:13] offset:512 nt
	v_mul_f32_e32 v196, v68, v150
	v_mul_f32_e32 v197, v69, v150
	v_mul_f32_e32 v198, v70, v150
	v_mul_f32_e32 v199, v71, v150
	v_mul_f32_e32 v200, v64, v151
	v_mul_f32_e32 v201, v65, v151
	v_mul_f32_e32 v202, v66, v151
	v_mul_f32_e32 v203, v67, v151
	v_fma_f32 v196, v196, v132, v140
	v_fma_f32 v197, v197, v133, v141
	v_fma_f32 v198, v198, v134, v142
	v_fma_f32 v199, v199, v135, v143
	v_fma_f32 v200, v200, v132, v140
	v_fma_f32 v201, v201, v133, v141
	v_fma_f32 v202, v202, v134, v142
	v_fma_f32 v203, v203, v135, v143
	v_cvt_pk_bf16_f32 v196, v196, v197
	v_cvt_pk_bf16_f32 v197, v198, v199
	v_cvt_pk_bf16_f32 v200, v200, v201
	v_cvt_pk_bf16_f32 v201, v202, v203
	v_add_u32_e32 v192, 0x18000, v177
	v_add_u32_e32 v193, 0x1c000, v177
	global_store_dwordx2 v192, v[196:197], s[94:95] offset:256
	global_store_dwordx2 v193, v[200:201], s[94:95] offset:256
	v_mov_b32_e32 v188, v60
	v_mov_b32_e32 v189, v61
	v_mov_b32_e32 v190, v62
	v_mov_b32_e32 v191, v63
	v_mov_b32_dpp v60, v56 row_ror:8 row_mask:0xf bank_mask:0xc
	v_mov_b32_dpp v61, v57 row_ror:8 row_mask:0xf bank_mask:0xc
	v_mov_b32_dpp v62, v58 row_ror:8 row_mask:0xf bank_mask:0xc
	v_mov_b32_dpp v63, v59 row_ror:8 row_mask:0xf bank_mask:0xc
	v_mov_b32_dpp v56, v188 row_ror:8 row_mask:0xf bank_mask:0x3
	v_mov_b32_dpp v57, v189 row_ror:8 row_mask:0xf bank_mask:0x3
	v_mov_b32_dpp v58, v190 row_ror:8 row_mask:0xf bank_mask:0x3
	v_mov_b32_dpp v59, v191 row_ror:8 row_mask:0xf bank_mask:0x3
	v_add_u32_e32 v192, 0x80000, v176
	v_add_u32_e32 v193, 0x88000, v176
	global_store_dwordx4 v192, v[60:63], s[12:13] nt
	global_store_dwordx4 v193, v[56:59], s[12:13] nt
	v_mul_f32_e32 v196, v60, v152
	v_mul_f32_e32 v197, v61, v152
	v_mul_f32_e32 v198, v62, v152
	v_mul_f32_e32 v199, v63, v152
	v_mul_f32_e32 v200, v56, v153
	v_mul_f32_e32 v201, v57, v153
	v_mul_f32_e32 v202, v58, v153
	v_mul_f32_e32 v203, v59, v153
	v_fma_f32 v196, v196, v128, v136
	v_fma_f32 v197, v197, v129, v137
	v_fma_f32 v198, v198, v130, v138
	v_fma_f32 v199, v199, v131, v139
	v_fma_f32 v200, v200, v128, v136
	v_fma_f32 v201, v201, v129, v137
	v_fma_f32 v202, v202, v130, v138
	v_fma_f32 v203, v203, v131, v139
	v_cvt_pk_bf16_f32 v196, v196, v197
	v_cvt_pk_bf16_f32 v197, v198, v199
	v_cvt_pk_bf16_f32 v200, v200, v201
	v_cvt_pk_bf16_f32 v201, v202, v203
	v_add_u32_e32 v192, 0x40000, v177
	v_add_u32_e32 v193, 0x44000, v177
	global_store_dwordx2 v192, v[196:197], s[94:95]
	global_store_dwordx2 v193, v[200:201], s[94:95]
	v_mov_b32_e32 v188, v52
	v_mov_b32_e32 v189, v53
	v_mov_b32_e32 v190, v54
	v_mov_b32_e32 v191, v55
	v_mov_b32_dpp v52, v48 row_ror:8 row_mask:0xf bank_mask:0xc
	v_mov_b32_dpp v53, v49 row_ror:8 row_mask:0xf bank_mask:0xc
	v_mov_b32_dpp v54, v50 row_ror:8 row_mask:0xf bank_mask:0xc
	v_mov_b32_dpp v55, v51 row_ror:8 row_mask:0xf bank_mask:0xc
	v_mov_b32_dpp v48, v188 row_ror:8 row_mask:0xf bank_mask:0x3
	v_mov_b32_dpp v49, v189 row_ror:8 row_mask:0xf bank_mask:0x3
	v_mov_b32_dpp v50, v190 row_ror:8 row_mask:0xf bank_mask:0x3
	v_mov_b32_dpp v51, v191 row_ror:8 row_mask:0xf bank_mask:0x3
	v_add_u32_e32 v192, 0x80000, v176
	v_add_u32_e32 v193, 0x88000, v176
	global_store_dwordx4 v192, v[52:55], s[12:13] offset:512 nt
	global_store_dwordx4 v193, v[48:51], s[12:13] offset:512 nt
	v_mul_f32_e32 v196, v52, v152
	v_mul_f32_e32 v197, v53, v152
	v_mul_f32_e32 v198, v54, v152
	v_mul_f32_e32 v199, v55, v152
	v_mul_f32_e32 v200, v48, v153
	v_mul_f32_e32 v201, v49, v153
; __device__ __forceinline__ unsigned cvt_pk_bf16(float lo, float hi) { unsigned r; asm volatile("v_cvt_pk_bf16_f32 %0, %1, %2" : "=v"(r) : "v"(lo), "v"(hi)); return r; }
;     __device__ __forceinline__ void fused(f32x4 (&acc)[2][2][4][2], const Unit& u, int wr, int wc, int fr, int fq, PG8_LAS unsigned char* lds, int wid, int lane) const {
;     ...
;         {
;             f32x4 g[2][2], sv[2][2];
; #pragma unroll
;             for (int bj = 0; bj < 2; ++bj)
; #pragma unroll
;                 for (int n = 0; n < 2; ++n) { g[bj][n] = *(const f32x4*)(gv2 + col0 + bj * HALF + n * 16); sv[bj][n] = *(const f32x4*)(sv2 + col0 + bj * HALF + n * 16); }
; #pragma unroll
;             for (int ai = 0; ai < 2; ++ai)
; #pragma unroll
;                 for (int m = 0; m < 4; ++m) { const int r = ai * HALF + wr * 64 + m * 16 + fr; const float rs = S[r]; const size_t off = (size_t)(row_off + u.pm * BM + r) * DM + col0;
; #pragma unroll
;                     for (int bj = 0; bj < 2; ++bj)
; #pragma unroll
;                         for (int n = 0; n < 2; ++n) { const f32x4 x1 = acc[ai][bj][m][n]; *(f32x4*)(out + off + bj * HALF + n * 16) = x1;
;                             const f32x4 o = x1 * rs * g[bj][n] + sv[bj][n]; u32x2 w; w.x = cvt_pk_bf16(o[0], o[1]); w.y = cvt_pk_bf16(o[2], o[3]); *(u32x2*)(xn + off + bj * HALF + n * 16) = w; }
;                     asm volatile("" ::: "memory"); }
	v_mul_f32_e32 v202, v50, v153
	v_mul_f32_e32 v203, v51, v153
	v_fma_f32 v196, v196, v132, v140
	v_fma_f32 v197, v197, v133, v141
	v_fma_f32 v198, v198, v134, v142
	v_fma_f32 v199, v199, v135, v143
	v_fma_f32 v200, v200, v132, v140
	v_fma_f32 v201, v201, v133, v141
	v_fma_f32 v202, v202, v134, v142
	v_fma_f32 v203, v203, v135, v143
	v_cvt_pk_bf16_f32 v196, v196, v197
	v_cvt_pk_bf16_f32 v197, v198, v199
	v_cvt_pk_bf16_f32 v200, v200, v201
	v_cvt_pk_bf16_f32 v201, v202, v203
	v_add_u32_e32 v192, 0x40000, v177
	v_add_u32_e32 v193, 0x44000, v177
	global_store_dwordx2 v192, v[196:197], s[94:95] offset:256
	global_store_dwordx2 v193, v[200:201], s[94:95] offset:256
	v_mov_b32_e32 v188, v44
	v_mov_b32_e32 v189, v45
	v_mov_b32_e32 v190, v46
	v_mov_b32_e32 v191, v47
	v_mov_b32_dpp v44, v40 row_ror:8 row_mask:0xf bank_mask:0xc
	v_mov_b32_dpp v45, v41 row_ror:8 row_mask:0xf bank_mask:0xc
	v_mov_b32_dpp v46, v42 row_ror:8 row_mask:0xf bank_mask:0xc
	v_mov_b32_dpp v47, v43 row_ror:8 row_mask:0xf bank_mask:0xc
	v_mov_b32_dpp v40, v188 row_ror:8 row_mask:0xf bank_mask:0x3
	v_mov_b32_dpp v41, v189 row_ror:8 row_mask:0xf bank_mask:0x3
	v_mov_b32_dpp v42, v190 row_ror:8 row_mask:0xf bank_mask:0x3
	v_mov_b32_dpp v43, v191 row_ror:8 row_mask:0xf bank_mask:0x3
	v_add_u32_e32 v192, 0x90000, v176
	v_add_u32_e32 v193, 0x98000, v176
	global_store_dwordx4 v192, v[44:47], s[12:13] nt
	global_store_dwordx4 v193, v[40:43], s[12:13] nt
	v_mul_f32_e32 v196, v44, v154
	v_mul_f32_e32 v197, v45, v154
	v_mul_f32_e32 v198, v46, v154
	v_mul_f32_e32 v199, v47, v154
	v_mul_f32_e32 v200, v40, v155
	v_mul_f32_e32 v201, v41, v155
	v_mul_f32_e32 v202, v42, v155
	v_mul_f32_e32 v203, v43, v155
	v_fma_f32 v196, v196, v128, v136
	v_fma_f32 v197, v197, v129, v137
	v_fma_f32 v198, v198, v130, v138
	v_fma_f32 v199, v199, v131, v139
	v_fma_f32 v200, v200, v128, v136
	v_fma_f32 v201, v201, v129, v137
	v_fma_f32 v202, v202, v130, v138
	v_fma_f32 v203, v203, v131, v139
	v_cvt_pk_bf16_f32 v196, v196, v197
	v_cvt_pk_bf16_f32 v197, v198, v199
	v_cvt_pk_bf16_f32 v200, v200, v201
	v_cvt_pk_bf16_f32 v201, v202, v203
	v_add_u32_e32 v192, 0x48000, v177
	v_add_u32_e32 v193, 0x4c000, v177
	global_store_dwordx2 v192, v[196:197], s[94:95]
	global_store_dwordx2 v193, v[200:201], s[94:95]
	v_mov_b32_e32 v188, v36
	v_mov_b32_e32 v189, v37
	v_mov_b32_e32 v190, v38
	v_mov_b32_e32 v191, v39
	v_mov_b32_dpp v36, v32 row_ror:8 row_mask:0xf bank_mask:0xc
	v_mov_b32_dpp v37, v33 row_ror:8 row_mask:0xf bank_mask:0xc
	v_mov_b32_dpp v38, v34 row_ror:8 row_mask:0xf bank_mask:0xc
	v_mov_b32_dpp v39, v35 row_ror:8 row_mask:0xf bank_mask:0xc
	v_mov_b32_dpp v32, v188 row_ror:8 row_mask:0xf bank_mask:0x3
	v_mov_b32_dpp v33, v189 row_ror:8 row_mask:0xf bank_mask:0x3
	v_mov_b32_dpp v34, v190 row_ror:8 row_mask:0xf bank_mask:0x3
	v_mov_b32_dpp v35, v191 row_ror:8 row_mask:0xf bank_mask:0x3
	v_add_u32_e32 v192, 0x90000, v176
	v_add_u32_e32 v193, 0x98000, v176
	global_store_dwordx4 v192, v[36:39], s[12:13] offset:512 nt
	global_store_dwordx4 v193, v[32:35], s[12:13] offset:512 nt
	v_mul_f32_e32 v196, v36, v154
	v_mul_f32_e32 v197, v37, v154
	v_mul_f32_e32 v198, v38, v154
	v_mul_f32_e32 v199, v39, v154
	v_mul_f32_e32 v200, v32, v155
	v_mul_f32_e32 v201, v33, v155
	v_mul_f32_e32 v202, v34, v155
	v_mul_f32_e32 v203, v35, v155
	v_fma_f32 v196, v196, v132, v140
	v_fma_f32 v197, v197, v133, v141
	v_fma_f32 v198, v198, v134, v142
	v_fma_f32 v199, v199, v135, v143
	v_fma_f32 v200, v200, v132, v140
	v_fma_f32 v201, v201, v133, v141
	v_fma_f32 v202, v202, v134, v142
	v_fma_f32 v203, v203, v135, v143
	v_cvt_pk_bf16_f32 v196, v196, v197
	v_cvt_pk_bf16_f32 v197, v198, v199
	v_cvt_pk_bf16_f32 v200, v200, v201
	v_cvt_pk_bf16_f32 v201, v202, v203
	v_add_u32_e32 v192, 0x48000, v177
	v_add_u32_e32 v193, 0x4c000, v177
	global_store_dwordx2 v192, v[196:197], s[94:95] offset:256
	global_store_dwordx2 v193, v[200:201], s[94:95] offset:256
	v_mov_b32_e32 v188, v28
	v_mov_b32_e32 v189, v29
	v_mov_b32_e32 v190, v30
	v_mov_b32_e32 v191, v31
	v_mov_b32_dpp v28, v24 row_ror:8 row_mask:0xf bank_mask:0xc
	v_mov_b32_dpp v29, v25 row_ror:8 row_mask:0xf bank_mask:0xc
	v_mov_b32_dpp v30, v26 row_ror:8 row_mask:0xf bank_mask:0xc
	v_mov_b32_dpp v31, v27 row_ror:8 row_mask:0xf bank_mask:0xc
	v_mov_b32_dpp v24, v188 row_ror:8 row_mask:0xf bank_mask:0x3
	v_mov_b32_dpp v25, v189 row_ror:8 row_mask:0xf bank_mask:0x3
	v_mov_b32_dpp v26, v190 row_ror:8 row_mask:0xf bank_mask:0x3
	v_mov_b32_dpp v27, v191 row_ror:8 row_mask:0xf bank_mask:0x3
	v_add_u32_e32 v192, 0xa0000, v176
	v_add_u32_e32 v193, 0xa8000, v176
	global_store_dwordx4 v192, v[28:31], s[12:13] nt
	global_store_dwordx4 v193, v[24:27], s[12:13] nt
	v_mul_f32_e32 v196, v28, v156
	v_mul_f32_e32 v197, v29, v156
	v_mul_f32_e32 v198, v30, v156
	v_mul_f32_e32 v199, v31, v156
	v_mul_f32_e32 v200, v24, v157
	v_mul_f32_e32 v201, v25, v157
	v_mul_f32_e32 v202, v26, v157
	v_mul_f32_e32 v203, v27, v157
	v_fma_f32 v196, v196, v128, v136
	v_fma_f32 v197, v197, v129, v137
	v_fma_f32 v198, v198, v130, v138
	v_fma_f32 v199, v199, v131, v139
	v_fma_f32 v200, v200, v128, v136
	v_fma_f32 v201, v201, v129, v137
	v_fma_f32 v202, v202, v130, v138
	v_fma_f32 v203, v203, v131, v139
; __device__ __forceinline__ unsigned cvt_pk_bf16(float lo, float hi) { unsigned r; asm volatile("v_cvt_pk_bf16_f32 %0, %1, %2" : "=v"(r) : "v"(lo), "v"(hi)); return r; }
;     __device__ __forceinline__ void fused(f32x4 (&acc)[2][2][4][2], const Unit& u, int wr, int wc, int fr, int fq, PG8_LAS unsigned char* lds, int wid, int lane) const {
;     ...
;         {
;             f32x4 g[2][2], sv[2][2];
; #pragma unroll
;             for (int bj = 0; bj < 2; ++bj)
; #pragma unroll
;                 for (int n = 0; n < 2; ++n) { g[bj][n] = *(const f32x4*)(gv2 + col0 + bj * HALF + n * 16); sv[bj][n] = *(const f32x4*)(sv2 + col0 + bj * HALF + n * 16); }
; #pragma unroll
;             for (int ai = 0; ai < 2; ++ai)
; #pragma unroll
;                 for (int m = 0; m < 4; ++m) { const int r = ai * HALF + wr * 64 + m * 16 + fr; const float rs = S[r]; const size_t off = (size_t)(row_off + u.pm * BM + r) * DM + col0;
; #pragma unroll
;                     for (int bj = 0; bj < 2; ++bj)
; #pragma unroll
;                         for (int n = 0; n < 2; ++n) { const f32x4 x1 = acc[ai][bj][m][n]; *(f32x4*)(out + off + bj * HALF + n * 16) = x1;
;                             const f32x4 o = x1 * rs * g[bj][n] + sv[bj][n]; u32x2 w; w.x = cvt_pk_bf16(o[0], o[1]); w.y = cvt_pk_bf16(o[2], o[3]); *(u32x2*)(xn + off + bj * HALF + n * 16) = w; }
;                     asm volatile("" ::: "memory"); }
;         }
;         asm volatile("s_waitcnt lgkmcnt(0)" ::: "memory"); __builtin_amdgcn_s_barrier(); asm volatile("" ::: "memory");
	v_cvt_pk_bf16_f32 v196, v196, v197
	v_cvt_pk_bf16_f32 v197, v198, v199
	v_cvt_pk_bf16_f32 v200, v200, v201
	v_cvt_pk_bf16_f32 v201, v202, v203
	v_add_u32_e32 v192, 0x50000, v177
	v_add_u32_e32 v193, 0x54000, v177
	global_store_dwordx2 v192, v[196:197], s[94:95]
	global_store_dwordx2 v193, v[200:201], s[94:95]
	v_mov_b32_e32 v188, v20
	v_mov_b32_e32 v189, v21
	v_mov_b32_e32 v190, v22
	v_mov_b32_e32 v191, v23
	v_mov_b32_dpp v20, v16 row_ror:8 row_mask:0xf bank_mask:0xc
	v_mov_b32_dpp v21, v17 row_ror:8 row_mask:0xf bank_mask:0xc
	v_mov_b32_dpp v22, v18 row_ror:8 row_mask:0xf bank_mask:0xc
	v_mov_b32_dpp v23, v19 row_ror:8 row_mask:0xf bank_mask:0xc
	v_mov_b32_dpp v16, v188 row_ror:8 row_mask:0xf bank_mask:0x3
	v_mov_b32_dpp v17, v189 row_ror:8 row_mask:0xf bank_mask:0x3
	v_mov_b32_dpp v18, v190 row_ror:8 row_mask:0xf bank_mask:0x3
	v_mov_b32_dpp v19, v191 row_ror:8 row_mask:0xf bank_mask:0x3
	v_add_u32_e32 v192, 0xa0000, v176
	v_add_u32_e32 v193, 0xa8000, v176
	global_store_dwordx4 v192, v[20:23], s[12:13] offset:512 nt
	global_store_dwordx4 v193, v[16:19], s[12:13] offset:512 nt
	v_mul_f32_e32 v196, v20, v156
	v_mul_f32_e32 v197, v21, v156
	v_mul_f32_e32 v198, v22, v156
	v_mul_f32_e32 v199, v23, v156
	v_mul_f32_e32 v200, v16, v157
	v_mul_f32_e32 v201, v17, v157
	v_mul_f32_e32 v202, v18, v157
	v_mul_f32_e32 v203, v19, v157
	v_fma_f32 v196, v196, v132, v140
	v_fma_f32 v197, v197, v133, v141
	v_fma_f32 v198, v198, v134, v142
	v_fma_f32 v199, v199, v135, v143
	v_fma_f32 v200, v200, v132, v140
	v_fma_f32 v201, v201, v133, v141
	v_fma_f32 v202, v202, v134, v142
	v_fma_f32 v203, v203, v135, v143
	v_cvt_pk_bf16_f32 v196, v196, v197
	v_cvt_pk_bf16_f32 v197, v198, v199
	v_cvt_pk_bf16_f32 v200, v200, v201
	v_cvt_pk_bf16_f32 v201, v202, v203
	v_add_u32_e32 v192, 0x50000, v177
	v_add_u32_e32 v193, 0x54000, v177
	global_store_dwordx2 v192, v[196:197], s[94:95] offset:256
	global_store_dwordx2 v193, v[200:201], s[94:95] offset:256
	v_mov_b32_e32 v188, v12
	v_mov_b32_e32 v189, v13
	v_mov_b32_e32 v190, v14
	v_mov_b32_e32 v191, v15
	v_mov_b32_dpp v12, v8 row_ror:8 row_mask:0xf bank_mask:0xc
	v_mov_b32_dpp v13, v9 row_ror:8 row_mask:0xf bank_mask:0xc
	v_mov_b32_dpp v14, v10 row_ror:8 row_mask:0xf bank_mask:0xc
	v_mov_b32_dpp v15, v11 row_ror:8 row_mask:0xf bank_mask:0xc
	v_mov_b32_dpp v8, v188 row_ror:8 row_mask:0xf bank_mask:0x3
	v_mov_b32_dpp v9, v189 row_ror:8 row_mask:0xf bank_mask:0x3
	v_mov_b32_dpp v10, v190 row_ror:8 row_mask:0xf bank_mask:0x3
	v_mov_b32_dpp v11, v191 row_ror:8 row_mask:0xf bank_mask:0x3
	v_add_u32_e32 v192, 0xb0000, v176
	v_add_u32_e32 v193, 0xb8000, v176
	global_store_dwordx4 v192, v[12:15], s[12:13] nt
	global_store_dwordx4 v193, v[8:11], s[12:13] nt
	v_mul_f32_e32 v196, v12, v158
	v_mul_f32_e32 v197, v13, v158
	v_mul_f32_e32 v198, v14, v158
	v_mul_f32_e32 v199, v15, v158
	v_mul_f32_e32 v200, v8, v159
	v_mul_f32_e32 v201, v9, v159
	v_mul_f32_e32 v202, v10, v159
	v_mul_f32_e32 v203, v11, v159
	v_fma_f32 v196, v196, v128, v136
	v_fma_f32 v197, v197, v129, v137
	v_fma_f32 v198, v198, v130, v138
	v_fma_f32 v199, v199, v131, v139
	v_fma_f32 v200, v200, v128, v136
	v_fma_f32 v201, v201, v129, v137
	v_fma_f32 v202, v202, v130, v138
	v_fma_f32 v203, v203, v131, v139
	v_cvt_pk_bf16_f32 v196, v196, v197
	v_cvt_pk_bf16_f32 v197, v198, v199
	v_cvt_pk_bf16_f32 v200, v200, v201
	v_cvt_pk_bf16_f32 v201, v202, v203
	v_add_u32_e32 v192, 0x58000, v177
	v_add_u32_e32 v193, 0x5c000, v177
	global_store_dwordx2 v192, v[196:197], s[94:95]
	global_store_dwordx2 v193, v[200:201], s[94:95]
	v_mov_b32_e32 v188, v4
	v_mov_b32_e32 v189, v5
	v_mov_b32_e32 v190, v6
	v_mov_b32_e32 v191, v7
	v_mov_b32_dpp v4, v0 row_ror:8 row_mask:0xf bank_mask:0xc
	v_mov_b32_dpp v5, v1 row_ror:8 row_mask:0xf bank_mask:0xc
	v_mov_b32_dpp v6, v2 row_ror:8 row_mask:0xf bank_mask:0xc
	v_mov_b32_dpp v7, v3 row_ror:8 row_mask:0xf bank_mask:0xc
	v_mov_b32_dpp v0, v188 row_ror:8 row_mask:0xf bank_mask:0x3
	v_mov_b32_dpp v1, v189 row_ror:8 row_mask:0xf bank_mask:0x3
	v_mov_b32_dpp v2, v190 row_ror:8 row_mask:0xf bank_mask:0x3
	v_mov_b32_dpp v3, v191 row_ror:8 row_mask:0xf bank_mask:0x3
	v_add_u32_e32 v192, 0xb0000, v176
	v_add_u32_e32 v193, 0xb8000, v176
	global_store_dwordx4 v192, v[4:7], s[12:13] offset:512 nt
	global_store_dwordx4 v193, v[0:3], s[12:13] offset:512 nt
	v_mul_f32_e32 v196, v4, v158
	v_mul_f32_e32 v197, v5, v158
	v_mul_f32_e32 v198, v6, v158
	v_mul_f32_e32 v199, v7, v158
	v_mul_f32_e32 v200, v0, v159
	v_mul_f32_e32 v201, v1, v159
	v_mul_f32_e32 v202, v2, v159
	v_mul_f32_e32 v203, v3, v159
	v_fma_f32 v196, v196, v132, v140
	v_fma_f32 v197, v197, v133, v141
	v_fma_f32 v198, v198, v134, v142
	v_fma_f32 v199, v199, v135, v143
	v_fma_f32 v200, v200, v132, v140
	v_fma_f32 v201, v201, v133, v141
	v_fma_f32 v202, v202, v134, v142
	v_fma_f32 v203, v203, v135, v143
	v_cvt_pk_bf16_f32 v196, v196, v197
	v_cvt_pk_bf16_f32 v197, v198, v199
	v_cvt_pk_bf16_f32 v200, v200, v201
	v_cvt_pk_bf16_f32 v201, v202, v203
	v_add_u32_e32 v192, 0x58000, v177
	v_add_u32_e32 v193, 0x5c000, v177
	global_store_dwordx2 v192, v[196:197], s[94:95] offset:256
	global_store_dwordx2 v193, v[200:201], s[94:95] offset:256
	s_waitcnt lgkmcnt(0)
	s_barrier
